# v055 + MERGE odd-workgroup start offset retuned from 11.0 to 8.5 us (half of the shortened segment period)
# speedup vs baseline: 1.0018x; 1.0018x over previous
.LBB0_1053:
	s_waitcnt lgkmcnt(0)
	s_barrier
	v_mbcnt_lo_u32_b32 v0, -1, 0
	v_mbcnt_hi_u32_b32 v0, -1, v0
	v_readlane_b32 s42, v255, 11
	s_mov_b32 s2, s55
	v_readlane_b32 s48, v255, 12
	s_mov_b32 s43, s84
	v_readlane_b32 s4, v255, 4
	v_readlane_b32 s6, v255, 6
	v_readlane_b32 s7, v255, 7
	s_and_b32 s41, s43, 1
	s_mov_b32 s10, s6
	s_mov_b32 s11, s7
	s_cmp_eq_u32 s41, 0
	v_readlane_b32 s5, v255, 5
	s_cbranch_scc1 .LBB0_1056
	s_memrealtime s[4:5]
	s_memrealtime s[0:1]
	v_mov_b64_e32 v[2:3], 0x351
	s_waitcnt lgkmcnt(0)
	s_sub_u32 s0, s0, s4
	s_subb_u32 s1, s1, s5
	v_cmp_gt_u64_e32 vcc, s[0:1], v[2:3]
	s_cbranch_vccnz .LBB0_1056
.LBB0_1055:
	s_sleep 8
	s_memrealtime s[0:1]
	v_mov_b64_e32 v[2:3], 0x352
	s_waitcnt lgkmcnt(0)
	s_sub_u32 s0, s0, s4
	s_subb_u32 s1, s1, s5
	v_cmp_lt_u64_e32 vcc, s[0:1], v[2:3]
	s_cbranch_vccnz .LBB0_1055
